# gla_c: S_f state tile fetched once per workgroup as whole rows at the unit top, staged into LDS (region dead after the q/k stage) and read as MFMA A fragments from there; S_b through an 8-quad global
# speedup vs baseline: 1.0120x; 1.0120x over previous
.LBB0_820:
	s_ashr_i32 s85, s84, 8
	s_and_b32 s45, s84, 63
	s_lshl_b32 s0, s85, 12
	s_lshl_b32 s1, s45, 6
	s_or_b32 s44, s0, s1
	v_or_b32_e32 v6, s44, v84
	v_mov_b64_e32 v[0:1], s[68:69]
	v_mad_i64_i32 v[2:3], s[0:1], v6, s79, v[0:1]
	v_lshl_add_u64 v[2:3], v[2:3], 0, v[30:31]
	v_or_b32_e32 v4, 16, v6
	v_add_co_u32_e32 v2, vcc, 0x1000, v2
	v_mad_i64_i32 v[4:5], s[0:1], v4, s79, v[0:1]
	s_nop 0
	v_addc_co_u32_e32 v3, vcc, 0, v3, vcc
	v_lshl_add_u64 v[4:5], v[4:5], 0, v[30:31]
	v_add_co_u32_e32 v4, vcc, 0x1000, v4
	s_bfe_u32 s86, s84, 0x20006
	s_nop 0
	v_addc_co_u32_e32 v5, vcc, 0, v5, vcc
	global_load_dwordx4 v[12:15], v[2:3], off offset:1344
	global_load_dwordx4 v[8:11], v[4:5], off offset:1344
	v_or_b32_e32 v2, 32, v6
	v_mad_i64_i32 v[2:3], s[0:1], v2, s79, v[0:1]
	v_lshl_add_u64 v[2:3], v[2:3], 0, v[30:31]
	v_or_b32_e32 v4, 48, v6
	v_add_co_u32_e32 v2, vcc, 0x1000, v2
	v_mad_i64_i32 v[0:1], s[0:1], v4, s79, v[0:1]
	s_nop 0
	v_addc_co_u32_e32 v3, vcc, 0, v3, vcc
	v_lshl_add_u64 v[0:1], v[0:1], 0, v[30:31]
	v_add_co_u32_e32 v0, vcc, 0x1000, v0
	s_lshl_b32 s70, s86, 9
	s_nop 0
	v_addc_co_u32_e32 v1, vcc, 0, v1, vcc
	global_load_dwordx4 v[4:7], v[2:3], off offset:1344
	s_nop 0
	global_load_dwordx4 v[0:3], v[0:1], off offset:1344
	v_lshl_add_u64 v[20:21], v[32:33], 0, s[70:71]
	v_lshlrev_b32_e32 v22, 2, v34
	v_mov_b32_e32 v16, 0
	v_mov_b32_e32 v17, 0
	v_mov_b32_e32 v18, 0
	v_mov_b32_e32 v19, 0
	s_lshl_b32 s98, s86, 7
	s_or_b32 s98, s98, s78
	v_or_b32_e32 v208, s98, v34
	v_mov_b32_e32 v209, v31
	v_lshl_add_u64 v[208:209], v[208:209], 2, s[90:91]
	global_load_dword v210, v[208:209], off
	global_load_dword v211, v[208:209], off offset:64
	s_and_saveexec_b64 s[0:1], s[2:3]
	v_mov_b32_e32 v23, v31
	v_lshl_add_u64 v[16:17], v[20:21], 0, v[22:23]
	v_add_co_u32_e32 v18, vcc, 0x1000, v16
	s_nop 1
	v_addc_co_u32_e32 v19, vcc, 0, v17, vcc
	v_add_co_u32_e32 v24, vcc, 0x2000, v16
	s_nop 1
	v_addc_co_u32_e32 v25, vcc, 0, v17, vcc
	v_add_co_u32_e32 v26, vcc, 0x3000, v16
	s_nop 1
	v_addc_co_u32_e32 v27, vcc, 0, v17, vcc
	global_load_dword v200, v[16:17], off offset:64
	global_load_dword v201, v[16:17], off offset:2112
	global_load_dword v202, v[18:19], off offset:64
	global_load_dword v203, v[18:19], off offset:2112
	global_load_dword v204, v[24:25], off offset:64
	global_load_dword v205, v[24:25], off offset:2112
	global_load_dword v206, v[26:27], off offset:64
	global_load_dword v207, v[26:27], off offset:2112
	global_load_dword v23, v[16:17], off
	s_nop 0
	global_load_dword v16, v[16:17], off offset:2048
	s_nop 0
	global_load_dword v17, v[18:19], off
	s_nop 0
	global_load_dword v18, v[18:19], off offset:2048
	s_nop 0
	global_load_dword v19, v[24:25], off
	s_nop 0
	global_load_dword v24, v[24:25], off offset:2048
	s_nop 0
	global_load_dword v25, v[26:27], off
	s_nop 0
	global_load_dword v26, v[26:27], off offset:2048
	s_or_b64 exec, exec, s[0:1]
	v_or_b32_e32 v190, s44, v144
	v_mov_b64_e32 v[174:175], s[68:69]
	v_mad_i64_i32 v[174:175], vcc, v190, s79, v[174:175]
	s_lshl_b32 s100, s86, 8
	s_mov_b32 s101, 0
	v_lshl_add_u64 v[174:175], v[174:175], 0, s[100:101]
	v_mov_b32_e32 v190, v48
	v_mov_b32_e32 v191, v31
	v_lshl_add_u64 v[174:175], v[174:175], 0, v[190:191]
	global_load_dwordx4 v[150:153], v[174:175], off offset:1344
	global_load_dwordx4 v[154:157], v[174:175], off offset:2368
	global_load_dwordx4 v[158:161], v[174:175], off offset:1472
	global_load_dwordx4 v[162:165], v[174:175], off offset:2496
	global_load_dwordx4 v[166:169], v[174:175], off offset:3392
	global_load_dwordx4 v[170:173], v[174:175], off offset:3520
	v_or_b32_e32 v190, s44, v97
	v_mov_b64_e32 v[186:187], s[68:69]
	v_mad_i64_i32 v[186:187], vcc, v190, s79, v[186:187]
	v_lshl_add_u64 v[186:187], v[186:187], 0, s[100:101]
	v_lshl_add_u64 v[186:187], v[186:187], 0, s[76:77]
	v_mov_b32_e32 v190, v50
	v_lshl_add_u64 v[188:189], v[186:187], 0, v[190:191]
	v_mov_b32_e32 v190, v52
	v_lshl_add_u64 v[186:187], v[186:187], 0, v[190:191]
	global_load_dwordx2 v[176:177], v[188:189], off
	global_load_dwordx2 v[178:179], v[188:189], off offset:32
	global_load_dwordx2 v[180:181], v[188:189], off offset:64
	global_load_dwordx2 v[182:183], v[186:187], off
	s_lshl_b32 s98, s85, 3
	s_lshl_b32 s99, s86, 1
	s_or_b32 s98, s99, s98
	s_ashr_i32 s99, s98, 31
	s_lshl_b64 s[98:99], s[98:99], 21
	s_add_u32 s98, s98, s52
	s_addc_u32 s99, s99, s53
	s_lshl_b32 s100, s45, 15
	s_add_u32 s98, s98, s100
	s_addc_u32 s99, s99, 0
	v_readlane_b32 s100, v244, 25
	v_lshrrev_b32_e32 v190, 4, v144
	v_and_b32_e32 v191, 15, v144
	v_lshl_add_u32 v190, s100, 4, v190
	v_lshlrev_b32_e32 v190, 8, v190
	v_lshl_add_u32 v190, v191, 4, v190
	global_load_dwordx4 v[192:195], v190, s[98:99]
	global_load_dwordx4 v[196:199], v190, s[98:99] offset:1024
	global_load_dwordx4 v[232:235], v190, s[98:99] offset:2048
	global_load_dwordx4 v[236:239], v190, s[98:99] offset:3072
	s_waitcnt vmcnt(14)
	s_and_saveexec_b64 s[0:1], s[2:3]
	v_cvt_pk_bf16_f32 v16, v23, v16
	v_cvt_pk_bf16_f32 v17, v17, v18
	v_cvt_pk_bf16_f32 v18, v19, v24
	v_cvt_pk_bf16_f32 v19, v25, v26

.LBB0_828:
	s_or_b64 exec, exec, s[0:1]
	s_waitcnt lgkmcnt(1)
	v_lshl_add_u32 v56, v126, 2, 0
	v_add_u32_e32 v56, 0x10600, v56
	ds_write_b32 v56, v125
	s_waitcnt lgkmcnt(0)
	s_barrier
	ds_read_b32 v56, v88 offset:1024
	s_waitcnt lgkmcnt(0)
	v_cndmask_b32_e64 v57, 0, v56, s[8:9]
	v_cndmask_b32_e64 v58, 0, v56, s[10:11]
	v_cndmask_b32_e64 v57, v58, v57, s[4:5]
	v_add_f32_e32 v2, v2, v57
	v_add_f32_e32 v3, v3, v57
	v_add_f32_e32 v4, v4, v57
	v_add_f32_e32 v5, v5, v57
	v_add_f32_e32 v6, v6, v57
	v_add_f32_e32 v7, v7, v57
	v_add_f32_e32 v8, v8, v57
	v_add_f32_e32 v9, v9, v57
	v_add_f32_e32 v10, v10, v57
	v_add_f32_e32 v11, v11, v57
	v_add_f32_e32 v12, v12, v57
	v_add_f32_e32 v13, v13, v57
	ds_write2_b32 v49, v2, v3 offset0:2 offset1:131
	ds_write2_b32 v51, v4, v5 offset0:4 offset1:133
	ds_write2_b32 v53, v6, v7 offset0:6 offset1:135
	ds_write2_b32 v114, v8, v9 offset0:8 offset1:137
	ds_write2_b32 v117, v10, v11 offset0:10 offset1:139
	ds_write2_b32 v120, v12, v13 offset0:12 offset1:141
	v_add_f32_e32 v2, v0, v57
	v_add_f32_e32 v1, v1, v57
	v_add_f32_e32 v14, v14, v57
	v_add_f32_e32 v15, v15, v57
	v_add_f32_e32 v16, v16, v57
	v_add_f32_e32 v17, v17, v57
	v_add_f32_e32 v18, v18, v57
	v_add_f32_e32 v19, v19, v57
	v_add_f32_e32 v20, v20, v57
	v_add_f32_e32 v21, v21, v57
	v_add_f32_e32 v22, v22, v57
	ds_write2_b32 v112, v2, v1 offset1:129
	ds_write2_b32 v115, v14, v15 offset0:14 offset1:143
	ds_write2_b32 v118, v16, v17 offset0:16 offset1:145
	ds_write2_b32 v121, v18, v19 offset0:18 offset1:147
	ds_write2_b32 v123, v20, v21 offset0:20 offset1:149
	v_add_f32_e32 v1, v23, v57
	ds_write2_b32 v124, v22, v1 offset0:22 offset1:151
	v_add_f32_e32 v1, v24, v57
	v_add_f32_e32 v2, v25, v57
	ds_write2_b32 v122, v1, v2 offset0:24 offset1:153
	v_add_f32_e32 v1, v26, v57
	v_add_f32_e32 v2, v27, v57
	ds_write2_b32 v119, v1, v2 offset0:26 offset1:155
	v_add_f32_e32 v1, v28, v57
	v_add_f32_e32 v2, v29, v57
	ds_write2_b32 v116, v1, v2 offset0:28 offset1:157
	v_add_f32_e32 v1, v54, v57
	v_add_f32_e32 v2, v55, v57
	ds_write2_b32 v113, v1, v2 offset0:30 offset1:159
	s_and_saveexec_b64 s[0:1], s[10:11]
	v_cndmask_b32_e64 v0, v0, v56, s[4:5]
	v_cndmask_b32_e64 v1, v56, v55, s[4:5]
	v_add_f32_e32 v0, v0, v1
	ds_write_b32 v89, v0
	s_or_b64 exec, exec, s[0:1]
	v_or_b32_e32 v2, s44, v144
	v_mov_b64_e32 v[0:1], s[68:69]
	v_mad_i64_i32 v[0:1], s[0:1], v2, s79, v[0:1]
	s_lshl_b32 s70, s70, 1
	v_lshl_add_u64 v[0:1], v[0:1], 0, s[70:71]
	v_mov_b32_e32 v49, v31
	v_lshl_add_u64 v[16:17], v[0:1], 0, v[48:49]
	s_waitcnt vmcnt(0) lgkmcnt(0)
	s_barrier
	v_mov_b32_e32 v12, v150
	v_mov_b32_e32 v13, v151
	v_mov_b32_e32 v14, v152
	v_mov_b32_e32 v15, v153
	v_mov_b32_e32 v8, v154
	v_mov_b32_e32 v9, v155
	v_mov_b32_e32 v10, v156
	v_mov_b32_e32 v11, v157
	v_add_u32_e32 v0, 0x8100, v90
	v_add_u32_e32 v1, 0x8108, v90
	v_add_u32_e32 v2, 0x8110, v90
	ds_read2_b32 v[18:19], v90 offset1:1
	ds_read2_b32 v[20:21], v90 offset0:2 offset1:3
	ds_read2_b32 v[22:23], v90 offset0:4 offset1:5
	ds_read2_b32 v[24:25], v0 offset1:1
	ds_read2_b32 v[26:27], v1 offset1:1
	ds_read2_b32 v[28:29], v2 offset1:1
	v_mov_b32_e32 v4, v158
	v_mov_b32_e32 v5, v159
	v_mov_b32_e32 v6, v160
	v_mov_b32_e32 v7, v161
	v_mov_b32_e32 v0, v162
	v_mov_b32_e32 v1, v163
	v_mov_b32_e32 v2, v164
	v_mov_b32_e32 v3, v165
	s_waitcnt lgkmcnt(5)
	v_mul_f32_e32 v49, 0x3fb8aa3b, v18
	v_mul_f32_e32 v51, 0xbfb8aa3b, v18
	v_mul_f32_e32 v53, 0x3fb8aa3b, v19
	v_mul_f32_e32 v54, 0xbfb8aa3b, v19
	s_waitcnt lgkmcnt(4)
	v_mul_f32_e32 v55, 0x3fb8aa3b, v20
	v_mul_f32_e32 v56, 0xbfb8aa3b, v20
	v_mul_f32_e32 v57, 0x3fb8aa3b, v21
	v_mul_f32_e32 v58, 0xbfb8aa3b, v21
	s_waitcnt lgkmcnt(3)
	v_mul_f32_e32 v59, 0x3fb8aa3b, v22
	v_mul_f32_e32 v60, 0xbfb8aa3b, v22
	v_mul_f32_e32 v61, 0x3fb8aa3b, v23
	v_mul_f32_e32 v62, 0xbfb8aa3b, v23
	s_waitcnt lgkmcnt(2)
	v_mul_f32_e32 v63, 0xbfb8aa3b, v25
	s_waitcnt lgkmcnt(1)
	v_mul_f32_e32 v64, 0x3fb8aa3b, v26
	v_mul_f32_e32 v65, 0xbfb8aa3b, v26
	v_mul_f32_e32 v66, 0x3fb8aa3b, v27
	v_mul_f32_e32 v67, 0xbfb8aa3b, v27
	v_exp_f32_e32 v18, v49
	v_exp_f32_e32 v20, v51
	v_mul_f32_e32 v49, 0x3fb8aa3b, v24
	v_mul_f32_e32 v51, 0xbfb8aa3b, v24
	v_exp_f32_e32 v19, v53
	v_exp_f32_e32 v21, v54
	v_mul_f32_e32 v53, 0x3fb8aa3b, v25
	v_exp_f32_e32 v22, v55
	v_exp_f32_e32 v24, v56
	v_exp_f32_e32 v23, v57
	v_exp_f32_e32 v25, v58
	v_exp_f32_e32 v26, v59
	v_exp_f32_e32 v54, v60
	v_exp_f32_e32 v27, v61
	v_exp_f32_e32 v55, v62
	v_exp_f32_e32 v59, v63
	v_exp_f32_e32 v60, v64
	v_exp_f32_e32 v62, v65
	v_exp_f32_e32 v61, v66
	v_exp_f32_e32 v63, v67
	s_waitcnt lgkmcnt(0)
	v_mul_f32_e32 v68, 0x3fb8aa3b, v28
	v_mul_f32_e32 v70, 0x3fb8aa3b, v29
	v_exp_f32_e32 v64, v68
	v_exp_f32_e32 v65, v70
	v_exp_f32_e32 v56, v49
	v_exp_f32_e32 v57, v53
	v_mul_f32_e32 v28, 0xbfb8aa3b, v28
	v_exp_f32_e32 v28, v28
	v_exp_f32_e32 v58, v51
	s_lshl_b32 s1, s86, 1
	s_lshl_b32 s45, s45, 15
	v_lshlrev_b32_e32 v66, 16, v12
	v_and_b32_e32 v67, 0xffff0000, v12
	v_lshlrev_b32_e32 v12, 16, v13
	v_and_b32_e32 v13, 0xffff0000, v13
	v_lshlrev_b32_e32 v68, 16, v8
	v_and_b32_e32 v69, 0xffff0000, v8
	v_lshlrev_b32_e32 v8, 16, v9
	v_and_b32_e32 v9, 0xffff0000, v9
	v_pk_mul_f32 v[66:67], v[66:67], s[74:75] op_sel_hi:[1,0]
	v_pk_mul_f32 v[12:13], v[12:13], s[74:75] op_sel_hi:[1,0]
	v_pk_mul_f32 v[62:63], v[62:63], v[8:9]
	v_pk_mul_f32 v[24:25], v[24:25], v[8:9]
	v_pk_mul_f32 v[8:9], v[66:67], v[18:19]
	v_pk_mul_f32 v[18:19], v[12:13], v[60:61]
	v_pk_mul_f32 v[12:13], v[12:13], v[22:23]
	v_lshlrev_b32_e32 v22, 16, v14
	v_and_b32_e32 v23, 0xffff0000, v14
	v_mul_f32_e32 v14, 0xbfb8aa3b, v29
	v_pk_mul_f32 v[22:23], v[22:23], s[74:75] op_sel_hi:[1,0]
	v_exp_f32_e32 v29, v14
	v_add_u32_e32 v14, 24, v90
	v_pk_mul_f32 v[60:61], v[22:23], v[64:65]
	v_pk_mul_f32 v[22:23], v[22:23], v[26:27]
	ds_read2st64_b32 v[26:27], v14 offset1:129
	v_pk_mul_f32 v[56:57], v[66:67], v[56:57]
	ds_read2st64_b32 v[66:67], v91 offset1:129
	v_lshlrev_b32_e32 v64, 16, v10
	v_and_b32_e32 v65, 0xffff0000, v10
	s_waitcnt lgkmcnt(1)
	v_mul_f32_e32 v10, 0x3fb8aa3b, v26
	v_pk_mul_f32 v[28:29], v[28:29], v[64:65]
	v_pk_mul_f32 v[54:55], v[54:55], v[64:65]
	v_exp_f32_e32 v64, v10
	v_mul_f32_e32 v10, 0xbfb8aa3b, v26
	v_exp_f32_e32 v26, v10
	v_mul_f32_e32 v10, 0x3fb8aa3b, v27
	v_pk_mul_f32 v[58:59], v[58:59], v[68:69]
	v_pk_mul_f32 v[20:21], v[20:21], v[68:69]
	v_exp_f32_e32 v68, v10
	v_mul_f32_e32 v10, 0xbfb8aa3b, v27
	v_exp_f32_e32 v14, v10
	s_waitcnt lgkmcnt(0)
	v_mul_f32_e32 v10, 0x3fb8aa3b, v66
	v_exp_f32_e32 v65, v10
	v_mul_f32_e32 v10, 0xbfb8aa3b, v66
	v_exp_f32_e32 v27, v10
	v_mul_f32_e32 v10, 0x3fb8aa3b, v67
	v_exp_f32_e32 v69, v10
	v_mul_f32_e32 v10, 0xbfb8aa3b, v67
	v_lshlrev_b32_e32 v70, 16, v15
	v_and_b32_e32 v71, 0xffff0000, v15
	v_exp_f32_e32 v15, v10
	v_pk_mul_f32 v[70:71], v[70:71], s[74:75] op_sel_hi:[1,0]
	v_lshlrev_b32_e32 v10, 16, v11
	v_pk_mul_f32 v[64:65], v[70:71], v[64:65]
	v_and_b32_e32 v11, 0xffff0000, v11
	v_pk_mul_f32 v[14:15], v[14:15], v[10:11]
	v_pk_mul_f32 v[26:27], v[26:27], v[10:11]
	v_cvt_pk_bf16_f32 v8, v8, v9
	v_cvt_pk_bf16_f32 v9, v12, v13
	v_cvt_pk_bf16_f32 v10, v22, v23
	v_cvt_pk_bf16_f32 v11, v64, v65
	v_pk_mul_f32 v[68:69], v[70:71], v[68:69]
	ds_write_b128 v92, v[8:11]
	v_cvt_pk_bf16_f32 v8, v20, v21
	v_cvt_pk_bf16_f32 v9, v24, v25
	v_cvt_pk_bf16_f32 v10, v54, v55
	v_cvt_pk_bf16_f32 v11, v26, v27
	ds_write_b128 v92, v[8:11] offset:17408
	v_cvt_pk_bf16_f32 v8, v56, v57
	v_cvt_pk_bf16_f32 v9, v18, v19
	v_cvt_pk_bf16_f32 v10, v60, v61
	v_cvt_pk_bf16_f32 v11, v68, v69
	ds_write_b128 v92, v[8:11] offset:34816
	v_cvt_pk_bf16_f32 v8, v58, v59
	v_cvt_pk_bf16_f32 v9, v62, v63
	v_cvt_pk_bf16_f32 v10, v28, v29
	v_cvt_pk_bf16_f32 v11, v14, v15
	ds_write_b128 v92, v[8:11] offset:52224
	ds_read2_b32 v[8:9], v90 offset0:64 offset1:65
	v_add_u32_e32 v10, 0x8200, v90
	ds_read2_b32 v[10:11], v10 offset1:1
	ds_read2_b32 v[12:13], v90 offset0:66 offset1:67
	ds_read2_b32 v[14:15], v90 offset0:68 offset1:69
	ds_read2_b32 v[18:19], v90 offset0:70 offset1:71
	v_add_u32_e32 v21, 0x8208, v90
	v_add_u32_e32 v24, 0x8210, v90
	v_add_u32_e32 v26, 0x8218, v90
	ds_read2_b32 v[22:23], v21 offset1:1
	ds_read2_b32 v[24:25], v24 offset1:1
	ds_read2_b32 v[26:27], v26 offset1:1
	s_waitcnt lgkmcnt(6)
	v_mul_f32_e32 v21, 0x3fb8aa3b, v10
	v_mul_f32_e32 v20, 0x3fb8aa3b, v8
	v_exp_f32_e32 v28, v21
	v_mul_f32_e32 v21, 0x3fb8aa3b, v9
	v_mul_f32_e32 v29, 0x3fb8aa3b, v11
	v_exp_f32_e32 v20, v20
	v_mul_f32_e32 v8, 0xbfb8aa3b, v8
	v_mul_f32_e32 v10, 0xbfb8aa3b, v10
	v_exp_f32_e32 v21, v21
	v_mul_f32_e32 v9, 0xbfb8aa3b, v9
	v_exp_f32_e32 v29, v29
	v_lshlrev_b32_e32 v54, 16, v4
	v_and_b32_e32 v55, 0xffff0000, v4
	v_mul_f32_e32 v4, 0xbfb8aa3b, v11
	v_exp_f32_e32 v8, v8
	v_exp_f32_e32 v10, v10
	v_exp_f32_e32 v9, v9
	v_exp_f32_e32 v11, v4
	v_pk_mul_f32 v[54:55], v[54:55], s[74:75] op_sel_hi:[1,0]
	v_lshlrev_b32_e32 v58, 16, v5
	v_pk_mul_f32 v[28:29], v[54:55], v[28:29]
	v_pk_mul_f32 v[20:21], v[54:55], v[20:21]
	v_lshlrev_b32_e32 v54, 16, v0
	v_and_b32_e32 v55, 0xffff0000, v0
	s_waitcnt lgkmcnt(5)
	v_mul_f32_e32 v0, 0x3fb8aa3b, v12
	v_pk_mul_f32 v[10:11], v[10:11], v[54:55]
	v_pk_mul_f32 v[8:9], v[8:9], v[54:55]
	v_exp_f32_e32 v54, v0
	v_mul_f32_e32 v0, 0xbfb8aa3b, v12
	v_exp_f32_e32 v12, v0
	s_waitcnt lgkmcnt(2)
	v_mul_f32_e32 v0, 0x3fb8aa3b, v22
	v_exp_f32_e32 v56, v0
	v_mul_f32_e32 v0, 0xbfb8aa3b, v22
	v_exp_f32_e32 v4, v0
	v_mul_f32_e32 v0, 0x3fb8aa3b, v13
	v_exp_f32_e32 v55, v0
	v_mul_f32_e32 v0, 0xbfb8aa3b, v13
	v_exp_f32_e32 v13, v0
	v_mul_f32_e32 v0, 0x3fb8aa3b, v23
	v_exp_f32_e32 v57, v0
	v_mul_f32_e32 v0, 0xbfb8aa3b, v23
	v_and_b32_e32 v59, 0xffff0000, v5
	v_exp_f32_e32 v5, v0
	v_lshlrev_b32_e32 v0, 16, v1
	v_and_b32_e32 v1, 0xffff0000, v1
	v_pk_mul_f32 v[12:13], v[12:13], v[0:1]
	v_pk_mul_f32 v[4:5], v[4:5], v[0:1]
	v_mul_f32_e32 v1, 0xbfb8aa3b, v14
	v_pk_mul_f32 v[58:59], v[58:59], s[74:75] op_sel_hi:[1,0]
	v_mul_f32_e32 v0, 0x3fb8aa3b, v14
	v_exp_f32_e32 v14, v1
	s_waitcnt lgkmcnt(1)
	v_mul_f32_e32 v1, 0x3fb8aa3b, v24
	v_pk_mul_f32 v[22:23], v[58:59], v[54:55]
	v_exp_f32_e32 v54, v1
	v_mul_f32_e32 v1, 0xbfb8aa3b, v24
	v_exp_f32_e32 v24, v1
	v_mul_f32_e32 v1, 0x3fb8aa3b, v15
	v_mul_f32_e32 v49, 0x3fb8aa3b, v25
	v_pk_mul_f32 v[56:57], v[58:59], v[56:57]
	v_exp_f32_e32 v0, v0
	v_exp_f32_e32 v1, v1
	v_mul_f32_e32 v15, 0xbfb8aa3b, v15
	v_exp_f32_e32 v55, v49
	v_lshlrev_b32_e32 v58, 16, v6
	v_and_b32_e32 v59, 0xffff0000, v6
	v_mul_f32_e32 v6, 0xbfb8aa3b, v25
	v_exp_f32_e32 v15, v15
	v_exp_f32_e32 v25, v6
	v_pk_mul_f32 v[58:59], v[58:59], s[74:75] op_sel_hi:[1,0]
	v_lshlrev_b32_e32 v62, 16, v7
	v_pk_mul_f32 v[54:55], v[58:59], v[54:55]
	v_pk_mul_f32 v[58:59], v[58:59], v[0:1]
	v_lshlrev_b32_e32 v0, 16, v2
	v_and_b32_e32 v1, 0xffff0000, v2
	v_pk_mul_f32 v[24:25], v[24:25], v[0:1]
	v_pk_mul_f32 v[14:15], v[14:15], v[0:1]
	v_mul_f32_e32 v1, 0xbfb8aa3b, v18
	v_mul_f32_e32 v0, 0x3fb8aa3b, v18
	v_exp_f32_e32 v18, v1
	s_waitcnt lgkmcnt(0)
	v_mul_f32_e32 v1, 0x3fb8aa3b, v26
	v_exp_f32_e32 v60, v1
	v_mul_f32_e32 v1, 0xbfb8aa3b, v26
	v_mul_f32_e32 v2, 0xbfb8aa3b, v19
	v_exp_f32_e32 v6, v1
	v_mul_f32_e32 v1, 0x3fb8aa3b, v19
	v_exp_f32_e32 v19, v2
	v_mul_f32_e32 v2, 0x3fb8aa3b, v27
	v_exp_f32_e32 v0, v0
	v_exp_f32_e32 v1, v1
	v_exp_f32_e32 v61, v2
	v_mul_f32_e32 v2, 0xbfb8aa3b, v27
	v_and_b32_e32 v63, 0xffff0000, v7
	v_exp_f32_e32 v7, v2
	v_pk_mul_f32 v[62:63], v[62:63], s[74:75] op_sel_hi:[1,0]
	v_cvt_pk_bf16_f32 v2, v58, v59
	v_pk_mul_f32 v[26:27], v[62:63], v[0:1]
	v_lshlrev_b32_e32 v0, 16, v3
	v_and_b32_e32 v1, 0xffff0000, v3
	v_pk_mul_f32 v[6:7], v[6:7], v[0:1]
	v_pk_mul_f32 v[18:19], v[18:19], v[0:1]
	v_cvt_pk_bf16_f32 v0, v20, v21
	v_cvt_pk_bf16_f32 v1, v22, v23
	v_cvt_pk_bf16_f32 v3, v26, v27
	v_pk_mul_f32 v[60:61], v[62:63], v[60:61]
	ds_write_b128 v92, v[0:3] offset:128
	v_cvt_pk_bf16_f32 v0, v8, v9
	v_cvt_pk_bf16_f32 v1, v12, v13
	v_cvt_pk_bf16_f32 v2, v14, v15
	v_cvt_pk_bf16_f32 v3, v18, v19
	ds_write_b128 v92, v[0:3] offset:17536
	v_cvt_pk_bf16_f32 v0, v28, v29
	v_cvt_pk_bf16_f32 v1, v56, v57
	v_cvt_pk_bf16_f32 v2, v54, v55
	v_cvt_pk_bf16_f32 v3, v60, v61
	ds_write_b128 v92, v[0:3] offset:34944
	v_cvt_pk_bf16_f32 v0, v10, v11
	v_cvt_pk_bf16_f32 v1, v4, v5
	v_cvt_pk_bf16_f32 v2, v24, v25
	v_cvt_pk_bf16_f32 v3, v6, v7
	ds_write_b128 v92, v[0:3] offset:52352
	s_waitcnt lgkmcnt(0)
	s_barrier
	v_mov_b32_e32 v0, v166
	v_mov_b32_e32 v1, v167
	v_mov_b32_e32 v2, v168
	v_mov_b32_e32 v3, v169
	v_mov_b32_e32 v4, v170
	v_mov_b32_e32 v5, v171
	v_mov_b32_e32 v6, v172
	v_mov_b32_e32 v7, v173
	v_readlane_b32 s99, v244, 25
	v_lshrrev_b32_e32 v210, 4, v144
	v_and_b32_e32 v211, 15, v144
	v_lshl_add_u32 v210, s99, 4, v210
	v_mul_u32_u24_e32 v210, 0x110, v210
	v_lshl_add_u32 v210, v211, 4, v210
	v_add_u32_e32 v210, 0x7000, v210
	ds_write_b128 v210, v[192:195]
	ds_write_b128 v210, v[196:199] offset:1088
	ds_write_b128 v210, v[232:235] offset:2176
	ds_write_b128 v210, v[236:239] offset:3264
	s_lshl_b32 s100, s85, 3
	s_lshl_b32 s101, s86, 1
	s_or_b32 s100, s101, s100
	s_or_b32 s100, s100, 1
	s_ashr_i32 s101, s100, 31
	s_lshl_b64 s[100:101], s[100:101], 21
	s_add_u32 s100, s100, s52
	s_addc_u32 s101, s101, s53
	s_add_u32 s100, s100, s45
	s_addc_u32 s101, s101, 0
	v_lshl_add_u64 v[210:211], v[36:37], 0, s[100:101]
	v_lshl_add_u64 v[210:211], v[210:211], 0, v[30:31]
	global_load_dwordx4 v[150:153], v[210:211], off
	global_load_dwordx4 v[154:157], v[210:211], off offset:64
	global_load_dwordx4 v[158:161], v[210:211], off offset:128
	global_load_dwordx4 v[162:165], v[210:211], off offset:192
	v_lshl_add_u64 v[210:211], v[38:39], 0, s[100:101]
	v_lshl_add_u64 v[210:211], v[210:211], 0, v[30:31]
	global_load_dwordx4 v[166:169], v[210:211], off
	global_load_dwordx4 v[170:173], v[210:211], off offset:64
	global_load_dwordx4 v[186:189], v[210:211], off offset:128
	global_load_dwordx4 v[190:193], v[210:211], off offset:192
	s_lshr_b32 s99, s99, 2
	v_lshrrev_b32_e32 v211, 4, v144
	v_and_b32_e32 v210, 15, v144
	v_lshl_add_u32 v210, s99, 6, v210
	v_mul_u32_u24_e32 v210, 0x110, v210
	v_lshl_add_u32 v210, v211, 4, v210
	v_add_u32_e32 v210, 0x7000, v210
	ds_write_b16 v103, v0
	ds_write_b16_d16_hi v103, v0 offset:144
	ds_write_b16 v103, v1 offset:288
	ds_write_b16_d16_hi v103, v1 offset:432
	ds_write_b16 v103, v2 offset:576
	ds_write_b16_d16_hi v103, v2 offset:720
	ds_write_b16 v103, v3 offset:864
	ds_write_b16_d16_hi v104, v3
	ds_write_b16 v103, v4 offset:9216
	ds_write_b16_d16_hi v103, v4 offset:9360
	ds_write_b16 v103, v5 offset:9504
	ds_write_b16_d16_hi v103, v5 offset:9648
	ds_write_b16 v103, v6 offset:9792
	ds_write_b16_d16_hi v103, v6 offset:9936
	ds_write_b16 v103, v7 offset:10080
	ds_write_b16_d16_hi v103, v7 offset:10224
	ds_read_b128 v[0:3], v93
	ds_read_b128 v[4:7], v95 offset:17408
	ds_read_b128 v[8:11], v94
	ds_read_b128 v[12:15], v93 offset:64
	ds_read_b128 v[16:19], v95 offset:17472
	s_waitcnt lgkmcnt(3)
	v_mfma_f32_16x16x32_bf16 v[0:3], v[0:3], v[4:7], 0
	ds_read_b128 v[4:7], v95 offset:52224
	ds_read_b128 v[20:23], v94 offset:64
	ds_read_b128 v[24:27], v95 offset:52288
	s_waitcnt lgkmcnt(2)
	v_mfma_f32_16x16x32_bf16 v[4:7], v[8:11], v[4:7], 0
	v_mfma_f32_16x16x32_bf16 v[0:3], v[12:15], v[16:19], v[0:3]
	ds_read_b128 v[8:11], v93 offset:128
	ds_read_b128 v[12:15], v95 offset:17536
	s_waitcnt lgkmcnt(2)
	v_mfma_f32_16x16x32_bf16 v[4:7], v[20:23], v[24:27], v[4:7]
	ds_read_b128 v[16:19], v94 offset:128
	ds_read_b128 v[20:23], v93 offset:192
	ds_read_b128 v[24:27], v95 offset:17600
	s_waitcnt lgkmcnt(3)
	v_mfma_f32_16x16x32_bf16 v[0:3], v[8:11], v[12:15], v[0:3]
	ds_read_b128 v[8:11], v95 offset:52352
	ds_read_b128 v[12:15], v94 offset:192
	ds_read_b128 v[54:57], v95 offset:52416
	s_waitcnt lgkmcnt(2)
	v_mfma_f32_16x16x32_bf16 v[4:7], v[16:19], v[8:11], v[4:7]
	v_mfma_f32_16x16x32_bf16 v[0:3], v[20:23], v[24:27], v[0:3]
	s_waitcnt lgkmcnt(0)
	v_mfma_f32_16x16x32_bf16 v[4:7], v[12:15], v[54:57], v[4:7]
	s_nop 5
	v_cndmask_b32_e64 v0, v0, 0, s[12:13]
	s_nop 0
	v_cndmask_b32_e64 v4, v4, 0, s[14:15]
	v_add_f32_e32 v0, v0, v4
	v_cvt_pk_bf16_f32 v0, v0, s0
	ds_write_b16 v105, v0 offset:18432
	v_cndmask_b32_e64 v0, v1, 0, s[16:17]
	v_cndmask_b32_e64 v1, 0, v5, s[12:13]
	v_add_f32_e32 v0, v0, v1
	v_cvt_pk_bf16_f32 v0, v0, s0
	ds_write_b16 v105, v0 offset:18576
	v_cndmask_b32_e64 v0, v2, 0, s[18:19]
	v_cndmask_b32_e64 v1, v6, 0, s[20:21]
	v_add_f32_e32 v0, v0, v1
	v_cvt_pk_bf16_f32 v0, v0, s0
	ds_write_b16 v105, v0 offset:18720
	v_cndmask_b32_e64 v0, v3, 0, s[22:23]
	v_cndmask_b32_e64 v1, v7, 0, s[24:25]
	v_add_f32_e32 v0, v0, v1
	v_cvt_pk_bf16_f32 v0, v0, s0
	ds_write_b16 v105, v0 offset:18864
	ds_read_b128 v[0:3], v93
	ds_read_b128 v[4:7], v96 offset:17408
	ds_read_b128 v[8:11], v94
	ds_read_b128 v[12:15], v93 offset:64
	ds_read_b128 v[16:19], v96 offset:17472
	s_waitcnt lgkmcnt(3)
	v_mfma_f32_16x16x32_bf16 v[0:3], v[0:3], v[4:7], 0
	ds_read_b128 v[4:7], v96 offset:52224
	ds_read_b128 v[20:23], v94 offset:64
	ds_read_b128 v[24:27], v96 offset:52288
	s_waitcnt lgkmcnt(2)
	v_mfma_f32_16x16x32_bf16 v[4:7], v[8:11], v[4:7], 0
	v_mfma_f32_16x16x32_bf16 v[0:3], v[12:15], v[16:19], v[0:3]
	ds_read_b128 v[8:11], v93 offset:128
	ds_read_b128 v[12:15], v96 offset:17536
	s_waitcnt lgkmcnt(2)
	v_mfma_f32_16x16x32_bf16 v[4:7], v[20:23], v[24:27], v[4:7]
	ds_read_b128 v[16:19], v94 offset:128
	ds_read_b128 v[20:23], v93 offset:192
	ds_read_b128 v[24:27], v96 offset:17600
	s_waitcnt lgkmcnt(3)
	v_mfma_f32_16x16x32_bf16 v[0:3], v[8:11], v[12:15], v[0:3]
	ds_read_b128 v[8:11], v96 offset:52352
	ds_read_b128 v[12:15], v94 offset:192
	ds_read_b128 v[54:57], v96 offset:52416
	s_waitcnt lgkmcnt(2)
	v_mfma_f32_16x16x32_bf16 v[4:7], v[16:19], v[8:11], v[4:7]
	v_mfma_f32_16x16x32_bf16 v[0:3], v[20:23], v[24:27], v[0:3]
	s_waitcnt lgkmcnt(0)
	v_mfma_f32_16x16x32_bf16 v[4:7], v[12:15], v[54:57], v[4:7]
	s_nop 5
	v_cndmask_b32_e64 v0, v0, 0, s[26:27]
	s_nop 0
	v_cndmask_b32_e64 v4, v4, 0, s[28:29]
	v_add_f32_e32 v0, v0, v4
	v_cvt_pk_bf16_f32 v0, v0, s0
	ds_write_b16 v105, v0 offset:18464
	v_cndmask_b32_e64 v0, v1, 0, s[30:31]
	v_cndmask_b32_e64 v1, 0, v5, s[26:27]
	v_add_f32_e32 v0, v0, v1
	v_cvt_pk_bf16_f32 v0, v0, s0
	ds_write_b16 v105, v0 offset:18608
	v_cndmask_b32_e64 v0, v2, 0, s[34:35]
	v_cndmask_b32_e64 v1, v6, 0, s[36:37]
	v_add_f32_e32 v0, v0, v1
	v_cvt_pk_bf16_f32 v0, v0, s0
	ds_write_b16 v105, v0 offset:18752
	v_cndmask_b32_e64 v0, v3, 0, s[38:39]
	v_cndmask_b32_e64 v1, v7, 0, s[40:41]
	v_add_f32_e32 v0, v0, v1
	v_cvt_pk_bf16_f32 v0, v0, s0
	s_lshl_b32 s0, s85, 3
	s_or_b32 s0, s1, s0
	s_ashr_i32 s1, s0, 31
	s_lshl_b64 s[46:47], s[0:1], 21
	s_or_b32 s0, s0, 1
	s_ashr_i32 s1, s0, 31
	s_lshl_b64 s[0:1], s[0:1], 21
	s_add_u32 s48, s52, s0
	s_addc_u32 s49, s53, s1
	s_add_u32 s0, s52, s46
	s_addc_u32 s1, s53, s47
	s_add_u32 s0, s0, s45
	s_addc_u32 s1, s1, 0
	v_lshl_add_u64 v[28:29], s[0:1], 0, v[30:31]
	v_lshl_add_u64 v[24:25], v[28:29], 0, v[36:37]
	ds_write_b16 v105, v0 offset:18896
	s_waitcnt lgkmcnt(0)
	s_barrier
	ds_read_b128 v[16:19], v106 offset:18432
	ds_read_b128 v[20:23], v106 offset:18496
	ds_read_b128 v[58:61], v107
	ds_read_b128 v[74:77], v107 offset:64
	ds_read_b128 v[54:57], v98
	ds_read_b128 v[62:65], v98 offset:64
	ds_read_b128 v[66:69], v98 offset:128
	ds_read_b128 v[70:73], v98 offset:192
	ds_read_b128 v[194:197], v210
	ds_read_b128 v[198:201], v210 offset:64
	ds_read_b128 v[202:205], v210 offset:128
	ds_read_b128 v[206:209], v210 offset:192
	s_waitcnt lgkmcnt(9)
	v_mfma_f32_16x16x32_bf16 v[12:15], v[58:61], v[16:19], 0
	s_waitcnt lgkmcnt(8)
	v_mfma_f32_16x16x32_bf16 v[12:15], v[74:77], v[20:23], v[12:15]
	s_waitcnt lgkmcnt(7)
	s_waitcnt lgkmcnt(3)
	v_mfma_f32_16x16x32_bf16 v[12:15], v[194:197], v[54:57], v[12:15]
	s_waitcnt lgkmcnt(6)
	s_waitcnt lgkmcnt(2)
	v_mfma_f32_16x16x32_bf16 v[12:15], v[198:201], v[62:65], v[12:15]
	s_waitcnt lgkmcnt(5)
	s_waitcnt lgkmcnt(1)
	v_mfma_f32_16x16x32_bf16 v[12:15], v[202:205], v[66:69], v[12:15]
	s_waitcnt lgkmcnt(4)
	s_waitcnt lgkmcnt(0)
	v_mfma_f32_16x16x32_bf16 v[12:15], v[206:209], v[70:73], v[12:15]
	ds_read_b128 v[24:27], v98 offset:34816
	ds_read_b128 v[78:81], v98 offset:34880
	ds_read_b128 v[114:117], v98 offset:34944
	ds_read_b128 v[118:121], v98 offset:35008
	ds_read_b128 v[58:61], v107 offset:2304
	ds_read_b128 v[74:77], v107 offset:2368
	ds_read_b128 v[228:231], v210 offset:4352
	ds_read_b128 v[232:235], v210 offset:4416
	ds_read_b128 v[236:239], v210 offset:4480
	ds_read_b128 v[240:243], v210 offset:4544
	s_waitcnt vmcnt(7) lgkmcnt(9)
	v_mfma_f32_16x16x32_bf16 v[12:15], v[150:153], v[24:27], v[12:15]
	v_lshl_add_u64 v[28:29], v[40:41], 0, s[100:101]
	v_lshl_add_u64 v[28:29], v[28:29], 0, v[30:31]
	global_load_dwordx4 v[150:153], v[28:29], off
	s_waitcnt vmcnt(7) lgkmcnt(8)
	v_mfma_f32_16x16x32_bf16 v[12:15], v[154:157], v[78:81], v[12:15]
	global_load_dwordx4 v[154:157], v[28:29], off offset:64
	s_waitcnt vmcnt(7) lgkmcnt(7)
	v_mfma_f32_16x16x32_bf16 v[12:15], v[158:161], v[114:117], v[12:15]
	global_load_dwordx4 v[158:161], v[28:29], off offset:128
	s_waitcnt vmcnt(7) lgkmcnt(6)
	v_mfma_f32_16x16x32_bf16 v[12:15], v[162:165], v[118:121], v[12:15]
	global_load_dwordx4 v[162:165], v[28:29], off offset:192
	s_waitcnt lgkmcnt(5)
	v_mfma_f32_16x16x32_bf16 v[8:11], v[58:61], v[16:19], 0
	s_waitcnt lgkmcnt(4)
	v_mfma_f32_16x16x32_bf16 v[8:11], v[74:77], v[20:23], v[8:11]
	s_waitcnt lgkmcnt(3)
	v_mfma_f32_16x16x32_bf16 v[8:11], v[228:231], v[54:57], v[8:11]
	s_waitcnt lgkmcnt(2)
	v_mfma_f32_16x16x32_bf16 v[8:11], v[232:235], v[62:65], v[8:11]
	v_mul_f32_e32 v130, v13, v13
	v_mul_f32_e32 v131, v15, v15
	v_fmac_f32_e32 v130, v12, v12
	v_fmac_f32_e32 v131, v14, v14
	v_add_f32_e32 v130, v130, v131
	v_mov_b32_e32 v132, v130
	s_waitcnt lgkmcnt(1)
	v_mfma_f32_16x16x32_bf16 v[8:11], v[236:239], v[66:69], v[8:11]
	s_waitcnt lgkmcnt(0)
	v_mfma_f32_16x16x32_bf16 v[8:11], v[240:243], v[70:73], v[8:11]
	ds_read_b128 v[58:61], v107 offset:4608
	ds_read_b128 v[74:77], v107 offset:4672
	ds_read_b128 v[194:197], v210 offset:8704
	ds_read_b128 v[198:201], v210 offset:8768
	ds_read_b128 v[202:205], v210 offset:8832
	ds_read_b128 v[206:209], v210 offset:8896
	s_waitcnt vmcnt(7)
	v_mfma_f32_16x16x32_bf16 v[8:11], v[166:169], v[24:27], v[8:11]
	v_lshl_add_u64 v[28:29], v[42:43], 0, s[100:101]
	v_lshl_add_u64 v[28:29], v[28:29], 0, v[30:31]
	global_load_dwordx4 v[166:169], v[28:29], off
	s_waitcnt vmcnt(7)
	v_mfma_f32_16x16x32_bf16 v[8:11], v[170:173], v[78:81], v[8:11]
	global_load_dwordx4 v[170:173], v[28:29], off offset:64
	s_waitcnt vmcnt(7)
	v_mfma_f32_16x16x32_bf16 v[8:11], v[186:189], v[114:117], v[8:11]
	global_load_dwordx4 v[186:189], v[28:29], off offset:128
	s_waitcnt vmcnt(7)
	v_mfma_f32_16x16x32_bf16 v[8:11], v[190:193], v[118:121], v[8:11]
	global_load_dwordx4 v[190:193], v[28:29], off offset:192
	s_waitcnt lgkmcnt(5)
	v_mfma_f32_16x16x32_bf16 v[4:7], v[58:61], v[16:19], 0
	s_waitcnt lgkmcnt(4)
	v_mfma_f32_16x16x32_bf16 v[4:7], v[74:77], v[20:23], v[4:7]
	s_waitcnt lgkmcnt(3)
	v_mfma_f32_16x16x32_bf16 v[4:7], v[194:197], v[54:57], v[4:7]
	s_waitcnt lgkmcnt(2)
	v_mfma_f32_16x16x32_bf16 v[4:7], v[198:201], v[62:65], v[4:7]
	v_mul_f32_e32 v130, v9, v9
	v_mul_f32_e32 v131, v11, v11
	v_fmac_f32_e32 v130, v8, v8
	v_fmac_f32_e32 v131, v10, v10
	v_add_f32_e32 v130, v130, v131
	v_add_f32_e32 v132, v132, v130
	s_waitcnt lgkmcnt(1)
	v_mfma_f32_16x16x32_bf16 v[4:7], v[202:205], v[66:69], v[4:7]
	s_waitcnt lgkmcnt(0)
	v_mfma_f32_16x16x32_bf16 v[4:7], v[206:209], v[70:73], v[4:7]
	ds_read_b128 v[58:61], v108
	ds_read_b128 v[74:77], v108 offset:64
	ds_read_b128 v[228:231], v210 offset:13056
	ds_read_b128 v[232:235], v210 offset:13120
	ds_read_b128 v[236:239], v210 offset:13184
	ds_read_b128 v[240:243], v210 offset:13248
	s_waitcnt vmcnt(7)
	v_mfma_f32_16x16x32_bf16 v[4:7], v[150:153], v[24:27], v[4:7]
	s_waitcnt vmcnt(6)
	v_mfma_f32_16x16x32_bf16 v[4:7], v[154:157], v[78:81], v[4:7]
	s_waitcnt vmcnt(5)
	v_mfma_f32_16x16x32_bf16 v[4:7], v[158:161], v[114:117], v[4:7]
	s_waitcnt vmcnt(4)
	v_mfma_f32_16x16x32_bf16 v[4:7], v[162:165], v[118:121], v[4:7]
	s_waitcnt lgkmcnt(5)
	v_mfma_f32_16x16x32_bf16 v[0:3], v[58:61], v[16:19], 0
	s_waitcnt lgkmcnt(4)
	v_mfma_f32_16x16x32_bf16 v[0:3], v[74:77], v[20:23], v[0:3]
	s_waitcnt lgkmcnt(3)
	v_mfma_f32_16x16x32_bf16 v[0:3], v[228:231], v[54:57], v[0:3]
	s_waitcnt lgkmcnt(2)
	v_mfma_f32_16x16x32_bf16 v[0:3], v[232:235], v[62:65], v[0:3]
	v_mul_f32_e32 v130, v5, v5
	v_mul_f32_e32 v131, v7, v7
	v_fmac_f32_e32 v130, v4, v4
	v_fmac_f32_e32 v131, v6, v6
	v_add_f32_e32 v130, v130, v131
	v_add_f32_e32 v132, v132, v130
	s_waitcnt lgkmcnt(1)
	v_mfma_f32_16x16x32_bf16 v[0:3], v[236:239], v[66:69], v[0:3]
	s_waitcnt lgkmcnt(0)
	v_mfma_f32_16x16x32_bf16 v[0:3], v[240:243], v[70:73], v[0:3]
	s_waitcnt vmcnt(3)
	v_mfma_f32_16x16x32_bf16 v[0:3], v[166:169], v[24:27], v[0:3]
	s_waitcnt vmcnt(2)
	v_mfma_f32_16x16x32_bf16 v[0:3], v[170:173], v[78:81], v[0:3]
	s_waitcnt vmcnt(1)
	v_mfma_f32_16x16x32_bf16 v[0:3], v[186:189], v[114:117], v[0:3]
	s_waitcnt vmcnt(0)
	v_mfma_f32_16x16x32_bf16 v[0:3], v[190:193], v[118:121], v[0:3]
	s_nop 7
	s_nop 1
	v_mul_f32_e32 v17, v1, v1
	v_mul_f32_e32 v18, v3, v3
	v_fmac_f32_e32 v17, v0, v0
	v_fmac_f32_e32 v18, v2, v2
	v_add_f32_e32 v17, v17, v18
	v_add_f32_e32 v16, v132, v17
	ds_bpermute_b32 v17, v101, v16
	s_waitcnt lgkmcnt(0)
	v_add_f32_e32 v16, v16, v17
	ds_bpermute_b32 v17, v102, v16
	s_and_saveexec_b64 s[0:1], s[42:43]
	s_cbranch_execz .LBB0_819
	s_waitcnt lgkmcnt(0)
	v_add_f32_e32 v16, v16, v17
	ds_write_b32 v99, v16 offset:27648
	s_branch .LBB0_819
